# MoBA bias-LUT reads batched: 16 serialized ds_read2+wait pairs replaced by one batch with two counted waits
# speedup vs baseline: 1.0017x; 1.0017x over previous
.LBB0_475:
	v_mov_b32_e32 v82, 0x4c0
	v_cndmask_b32_e64 v82, v82, 0, s[12:13]
	v_add_u32_e32 v84, v198, v82
	ds_read2_b32 v[98:99], v84 offset0:32 offset1:33
	ds_read2_b32 v[100:101], v84 offset0:34 offset1:35
	ds_read2_b32 v[102:103], v84 offset0:40 offset1:41
	ds_read2_b32 v[104:105], v84 offset0:42 offset1:43
	ds_read2_b32 v[106:107], v84 offset0:48 offset1:49
	ds_read2_b32 v[108:109], v84 offset0:50 offset1:51
	ds_read2_b32 v[110:111], v84 offset0:56 offset1:57
	ds_read2_b32 v[112:113], v84 offset0:58 offset1:59
	ds_read2_b32 v[82:83], v84 offset1:1
	ds_read2_b32 v[86:87], v84 offset0:2 offset1:3
	ds_read2_b32 v[88:89], v84 offset0:8 offset1:9
	ds_read2_b32 v[90:91], v84 offset0:10 offset1:11
	ds_read2_b32 v[92:93], v84 offset0:16 offset1:17
	ds_read2_b32 v[94:95], v84 offset0:18 offset1:19
	ds_read2_b32 v[96:97], v84 offset0:24 offset1:25
	ds_read2_b32 v[84:85], v84 offset0:26 offset1:27
	s_waitcnt lgkmcnt(8)
	v_pk_fma_f32 v[98:99], v[114:115], s[64:65], v[98:99] op_sel_hi:[1,0,1]
	v_pk_fma_f32 v[100:101], v[116:117], s[64:65], v[100:101] op_sel_hi:[1,0,1]
	v_pk_fma_f32 v[102:103], v[118:119], s[64:65], v[102:103] op_sel_hi:[1,0,1]
	v_pk_fma_f32 v[104:105], v[120:121], s[64:65], v[104:105] op_sel_hi:[1,0,1]
	v_pk_fma_f32 v[106:107], v[122:123], s[64:65], v[106:107] op_sel_hi:[1,0,1]
	v_pk_fma_f32 v[108:109], v[124:125], s[64:65], v[108:109] op_sel_hi:[1,0,1]
	v_pk_fma_f32 v[110:111], v[126:127], s[64:65], v[110:111] op_sel_hi:[1,0,1]
	v_pk_fma_f32 v[112:113], v[128:129], s[64:65], v[112:113] op_sel_hi:[1,0,1]
	s_waitcnt lgkmcnt(0)
	v_pk_fma_f32 v[66:67], v[66:67], s[64:65], v[82:83] op_sel_hi:[1,0,1]
	v_pk_fma_f32 v[68:69], v[68:69], s[64:65], v[86:87] op_sel_hi:[1,0,1]
	v_pk_fma_f32 v[70:71], v[70:71], s[64:65], v[88:89] op_sel_hi:[1,0,1]
	v_pk_fma_f32 v[72:73], v[72:73], s[64:65], v[90:91] op_sel_hi:[1,0,1]
	v_pk_fma_f32 v[74:75], v[74:75], s[64:65], v[92:93] op_sel_hi:[1,0,1]
	v_pk_fma_f32 v[76:77], v[76:77], s[64:65], v[94:95] op_sel_hi:[1,0,1]
	v_pk_fma_f32 v[78:79], v[78:79], s[64:65], v[96:97] op_sel_hi:[1,0,1]
	v_pk_fma_f32 v[80:81], v[80:81], s[64:65], v[84:85] op_sel_hi:[1,0,1]
	v_max_f32_e32 v82, v66, v67
	v_max3_f32 v82, v82, v68, v69
	v_max3_f32 v82, v82, v70, v71
	v_max3_f32 v82, v82, v72, v73
	v_max3_f32 v82, v82, v74, v75
	v_max3_f32 v82, v82, v76, v77
	v_max3_f32 v82, v82, v78, v79
	v_max3_f32 v82, v82, v80, v81
	v_max3_f32 v82, v82, v98, v99
	v_max3_f32 v82, v82, v100, v101
	v_max3_f32 v82, v82, v102, v103
	v_max3_f32 v82, v82, v104, v105
	v_max3_f32 v82, v82, v106, v107
	v_max3_f32 v82, v82, v108, v109
	v_max3_f32 v82, v82, v110, v111
	v_max3_f32 v82, v82, v112, v113
	v_mov_b32_e32 v83, v82
	s_nop 1
	v_permlane32_swap_b32_e32 v82, v83
	v_max_f32_e32 v83, v83, v83
	v_max_f32_e32 v82, v82, v82
	v_max_f32_e32 v82, v82, v83
	v_sub_f32_e32 v83, v82, v199
	v_cmp_ge_f32_e32 vcc, s60, v83
	v_max_f32_e32 v83, v199, v199
	v_max_f32_e32 v82, v83, v82
	v_sub_f32_e32 v83, v199, v82
	v_exp_f32_e32 v83, v83
	s_cmp_eq_u64 vcc, exec
	s_cselect_b64 vcc, -1, 0
	v_cndmask_b32_e32 v199, v82, v199, vcc
	v_cndmask_b32_e64 v208, v83, 1.0, vcc
	v_sub_f32_e32 v97, v81, v199
	v_sub_f32_e32 v96, v80, v199
	v_sub_f32_e32 v95, v79, v199
	v_sub_f32_e32 v94, v78, v199
	v_sub_f32_e32 v93, v77, v199
	v_sub_f32_e32 v92, v76, v199
	v_sub_f32_e32 v91, v75, v199
	v_sub_f32_e32 v90, v74, v199
	v_sub_f32_e32 v89, v73, v199
	v_sub_f32_e32 v88, v72, v199
	v_sub_f32_e32 v87, v71, v199
	v_sub_f32_e32 v86, v70, v199
	v_sub_f32_e32 v85, v69, v199
	v_sub_f32_e32 v84, v68, v199
	v_sub_f32_e32 v83, v67, v199
	v_sub_f32_e32 v82, v66, v199
	v_sub_f32_e32 v113, v113, v199
	v_sub_f32_e32 v112, v112, v199
	v_sub_f32_e32 v111, v111, v199
	v_sub_f32_e32 v110, v110, v199
	v_sub_f32_e32 v109, v109, v199
	v_sub_f32_e32 v108, v108, v199
	v_sub_f32_e32 v107, v107, v199
	v_sub_f32_e32 v106, v106, v199
	v_sub_f32_e32 v105, v105, v199
	v_sub_f32_e32 v104, v104, v199
	v_sub_f32_e32 v103, v103, v199
	v_sub_f32_e32 v102, v102, v199
	v_sub_f32_e32 v101, v101, v199
	v_sub_f32_e32 v100, v100, v199
	v_sub_f32_e32 v99, v99, v199
	v_sub_f32_e32 v98, v98, v199
	s_or_b64 exec, exec, s[0:1]
	v_cmp_gt_f32_e32 vcc, 1.0, v208
	s_cbranch_vccz .LBB0_479
